# SSD chunk loop: wave 0 runs its dt-scan block at raised issue priority (static priority lever)
# speedup vs baseline: 1.0021x; 1.0021x over previous
; __device__ __forceinline__ unsigned f2bf(float f) { return pk2(f, f) & 0xffffu; }
; __device__ __forceinline__ float rdlane(float v, int l) { return __builtin_bit_cast(float, __builtin_amdgcn_readlane(__builtin_bit_cast(int, v), l)); }
; #define BAR_LDS() asm volatile("s_waitcnt lgkmcnt(0)\n\ts_barrier" ::: "memory")
; template <bool DRY> __device__ __forceinline__ void ssd_unit(const Args& A, char* lds, int b, int h) {
;     ...
;         const float decay = __expf(DTA[64 + 63]);
;         BAR_LDS();
; #pragma unroll
;         for (int ks = 0; ks < 2; ++ks) { const bf16x8 gf = *(const bf16x8*)(GG + (lt * 16 + fr) * 72 + ks * 32 + 8 * fq);
; #pragma unroll
;             for (int pi = 0; pi < 2; ++pi) { const int p = (pt0 + pi) * 16 + fr; const bf16x8 xf = *(const bf16x8*)(XT + p * 72 + (((ks * 4 + fq) ^ ((p >> 3) & 7)) << 3)); ya[pi] = __builtin_amdgcn_mfma_f32_16x16x32_bf16(gf, xf, ya[pi], 0, 0, 0); } }
; #pragma unroll
;         for (int pi = 0; pi < 2; ++pi)
; #pragma unroll
;             for (int ni = 0; ni < 2; ++ni) sta[pi][ni] = sta[pi][ni] * decay;
; #pragma unroll
;         for (int ks = 0; ks < 2; ++ks) { bf16x8 bt[2];
; #pragma unroll
;             for (int ni = 0; ni < 2; ++ni) { const int n = (nt0 + ni) * 16 + fr; bt[ni] = *(const bf16x8*)(BST + n * 72 + (((ks * 4 + fq) ^ ((n >> 3) & 7)) << 3)); }
; #pragma unroll
;             for (int pi = 0; pi < 2; ++pi) { const int p = (pt0 + pi) * 16 + fr; const bf16x8 xw = *(const bf16x8*)(XWT + p * 72 + (((ks * 4 + fq) ^ ((p >> 3) & 7)) << 3));
; #pragma unroll
;                 for (int ni = 0; ni < 2; ++ni) sta[pi][ni] = __builtin_amdgcn_mfma_f32_16x16x32_bf16(xw, bt[ni], sta[pi][ni], 0, 0, 0); } }
; #pragma unroll
;         for (int pi = 0; pi < 2; ++pi)
; #pragma unroll
;             for (int ni = 0; ni < 2; ++ni)
; #pragma unroll
;                 for (int r = 0; r < 4; ++r) SBF[((pt0 + pi) * 16 + 4 * fq + r) * 136 + (nt0 + ni) * 16 + fr] = (bf16)f2bf(sta[pi][ni][r]);
;     ...
;         if (wave == 0 && c + 1 < SEQL / 64) { float* DN = DTA0 + ((c + 1) & 1) * 256; const float s = wave_scan(Ah * dtn, lane); const float tot = rdlane(s, 63);
;             DN[lane] = dtn; DN[64 + lane] = s; DN[128 + lane] = __expf(s); DN[192 + lane] = __expf(tot - s);
;             if (c + 2 < SEQL / 64) dtn = DT[(m0 + 128 + lane) * 16 + h]; }
.LBB0_837:
	s_or_b64 exec, exec, s[66:67]
	ds_write_b16 v119, v44
	v_mov_b32_e32 v44, s4
	ds_read_b32 v50, v85 offset:524
	ds_read_b32 v51, v44 offset:508
	s_and_b64 s[98:99], exec, s[26:27]
	s_cbranch_scc1 .Lssd_dts_skip
	s_setprio 2
	v_mul_f32_e64 v190, v69, -v100
	v_mov_b32_e32 v191, 0
	s_nop 1
	v_mov_b32_dpp v191, v190 row_shr:1 row_mask:0xf bank_mask:0xf
	v_fma_f32 v190, v69, -v100, v191
	v_cvt_f32_u32_e32 v192, v98
	s_nop 0
	v_add_f32_dpp v190, v190, v190 row_shr:2 row_mask:0xf bank_mask:0xf bound_ctrl:1
	v_min_f32_e32 v193, 1.0, v192
	v_add_f32_e32 v194, -1.0, v192
	v_add_f32_dpp v190, v190, v190 row_shr:4 row_mask:0xf bank_mask:0xf bound_ctrl:1
	v_add_f32_e32 v195, -2.0, v192
	v_med3_f32 v194, v194, 0, 1.0
	v_add_f32_dpp v190, v190, v190 row_shr:8 row_mask:0xf bank_mask:0xf bound_ctrl:1
	v_med3_f32 v195, v195, 0, 1.0
	s_nop 0
	v_readlane_b32 s98, v190, 15
	v_readlane_b32 s99, v190, 31
	v_readlane_b32 s100, v190, 47
	v_mul_f32_e32 v191, s98, v193
	v_fma_f32 v191, v194, s99, v191
	v_fma_f32 v191, v195, s100, v191
	v_add_f32_e32 v190, v190, v191
	v_mul_f32_e32 v191, 0x3fb8aa3b, v190
	v_readlane_b32 s98, v190, 63
	v_exp_f32_e32 v191, v191
	s_and_b32 s99, s0, 0x100
	v_sub_f32_e32 v192, s98, v190
	v_mul_f32_e32 v192, 0x3fb8aa3b, v192
	v_exp_f32_e32 v192, v192
	v_lshl_add_u32 v193, s99, 2, v126
	ds_write2st64_b32 v193, v69, v190 offset1:1
	ds_write2st64_b32 v193, v191, v192 offset0:2 offset1:3
	s_cmp_gt_u32 s1, 28
	s_cbranch_scc1 .Lssd_dts_skip
	global_load_dword v69, v[74:75], off
.Lssd_dts_skip:
	s_setprio 0
	s_waitcnt lgkmcnt(0)
	s_barrier
	s_waitcnt lgkmcnt(0)
	v_mul_f32_e32 v42, v42, v49
	v_mul_f32_e32 v38, v38, v49
	ds_read_b128 v[46:49], v113
	ds_read_b128 v[88:91], v106 offset:53248
	ds_read_b128 v[150:153], v104 offset:53248
	ds_read_b128 v[154:157], v113 offset:64
	ds_read_b128 v[158:161], v106 offset:62464
	v_mul_f32_e32 v41, v41, v45
	v_mul_f32_e32 v37, v37, v45
	v_mul_f32_e32 v40, v40, v83
	v_mul_f32_e32 v36, v36, v83
	v_mul_f32_e32 v43, v43, v50
	v_mul_f32_e32 v39, v39, v50
	v_mul_f32_e32 v82, 0x3fb8aa3b, v51
	s_waitcnt lgkmcnt(0)
	v_mfma_f32_16x16x32_bf16 v[40:43], v[46:49], v[88:91], v[40:43]
	ds_read_b128 v[88:91], v102 offset:53248
	ds_read_b128 v[162:165], v104 offset:62464
	v_exp_f32_e32 v82, v82
	v_add_u32_e32 v141, v127, v135
	v_mfma_f32_16x16x32_bf16 v[44:47], v[46:49], v[150:153], v[36:39]
	ds_read_b128 v[48:51], v101 offset:53248
	ds_read_b128 v[150:153], v102 offset:62464
	v_pk_mul_f32 v[14:15], v[14:15], v[82:83] op_sel_hi:[1,0]
	v_pk_mul_f32 v[12:13], v[12:13], v[82:83] op_sel_hi:[1,0]
	s_waitcnt lgkmcnt(0)
	v_mfma_f32_16x16x32_bf16 v[36:39], v[154:157], v[88:91], v[40:43]
	ds_read_b128 v[88:91], v103 offset:34816
	ds_read_b128 v[166:169], v101 offset:62464
	v_pk_mul_f32 v[10:11], v[10:11], v[82:83] op_sel_hi:[1,0]
	v_pk_mul_f32 v[8:9], v[8:9], v[82:83] op_sel_hi:[1,0]
	v_mfma_f32_16x16x32_bf16 v[40:43], v[154:157], v[48:51], v[44:47]
	v_mul_f32_e64 v6, v6, v82
	v_mul_f32_e64 v7, v7, v82
	v_pk_mul_f32 v[4:5], v[4:5], v[82:83] op_sel_hi:[1,0]
	v_pk_mul_f32 v[2:3], v[2:3], v[82:83] op_sel_hi:[1,0]
	ds_read_b128 v[44:47], v118 offset:34816
	s_waitcnt lgkmcnt(0)
	v_mfma_f32_16x16x32_bf16 v[12:15], v[158:161], v[88:91], v[12:15]
	v_mul_f32_e64 v0, v0, v82
	v_mul_f32_e64 v1, v1, v82
	v_add_u32_e32 v143, v128, v135
	v_add_u32_e32 v144, v127, v136
	v_mfma_f32_16x16x32_bf16 v[8:11], v[158:161], v[44:47], v[8:11]
	v_add_u32_e32 v140, v128, v136
	s_add_i32 s1, s1, 1
	v_mfma_f32_16x16x32_bf16 v[4:7], v[162:165], v[44:47], v[4:7]
	ds_read_b128 v[44:47], v121 offset:34816
	ds_read_b128 v[48:51], v122 offset:34816
	v_mfma_f32_16x16x32_bf16 v[0:3], v[162:165], v[88:91], v[0:3]
	v_lshlrev_b32_e32 v88, 16, v86
	v_and_b32_e32 v89, 0xffff0000, v86
	s_waitcnt lgkmcnt(0)
	v_mfma_f32_16x16x32_bf16 v[12:15], v[150:153], v[44:47], v[12:15]
	v_mfma_f32_16x16x32_bf16 v[8:11], v[150:153], v[48:51], v[8:11]
	v_mfma_f32_16x16x32_bf16 v[0:3], v[166:169], v[44:47], v[0:3]
	s_nop 5
	v_cvt_pk_bf16_f32 v44, v12, s0
	ds_write_b16 v141, v44
	v_cvt_pk_bf16_f32 v44, v13, s0
	ds_write_b16 v141, v44 offset:272
	v_cvt_pk_bf16_f32 v44, v14, s0
	ds_write_b16 v141, v44 offset:544
	v_cvt_pk_bf16_f32 v44, v15, s0
	ds_write_b16 v141, v44 offset:816
	v_cvt_pk_bf16_f32 v44, v8, s0
	ds_write_b16 v143, v44
	v_cvt_pk_bf16_f32 v44, v9, s0
	ds_write_b16 v143, v44 offset:272
	v_cvt_pk_bf16_f32 v44, v10, s0
	ds_write_b16 v143, v44 offset:544
	v_cvt_pk_bf16_f32 v44, v11, s0
	v_mfma_f32_16x16x32_bf16 v[4:7], v[166:169], v[48:51], v[4:7]
	ds_write_b16 v143, v44 offset:816
	v_cvt_pk_bf16_f32 v44, v0, s0
	ds_write_b16 v144, v44
	v_cvt_pk_bf16_f32 v44, v1, s0
	ds_write_b16 v144, v44 offset:272
	v_cvt_pk_bf16_f32 v44, v2, s0
	ds_write_b16 v144, v44 offset:544
	v_cvt_pk_bf16_f32 v44, v3, s0
	ds_write_b16 v144, v44 offset:816
	v_cvt_pk_bf16_f32 v44, v4, s0
	ds_write_b16 v140, v44
	v_cvt_pk_bf16_f32 v44, v5, s0
	ds_write_b16 v140, v44 offset:272
	v_cvt_pk_bf16_f32 v44, v6, s0
	ds_write_b16 v140, v44 offset:544
	v_cvt_pk_bf16_f32 v44, v7, s0
	v_lshlrev_b32_e32 v45, 16, v97
	ds_write_b16 v140, v44 offset:816
	v_mul_f32_e32 v44, 0xbfb8aa3b, v45
	v_exp_f32_e32 v44, v44
	ds_read_u16 v46, v110
	ds_read_u16 v47, v110 offset:144
	ds_read_u16 v48, v110 offset:288
	ds_read_u16 v97, v110 offset:432
	ds_read_u16 v82, v105
	ds_read_u16 v87, v105 offset:144
	ds_read_u16 v90, v105 offset:288
	ds_read_u16 v93, v105 offset:432
	s_waitcnt lgkmcnt(0)
; __device__ __forceinline__ unsigned f2bf(float f) { return pk2(f, f) & 0xffffu; }
; __device__ __forceinline__ float bf2f(unsigned short h) { return __uint_as_float(((unsigned)h) << 16); }
; __device__ __forceinline__ float row_sum16(float v) { v += dppf<0xB1>(v, v); v += dppf<0x4E>(v, v); v += dppf<0x141>(v, v); v += dppf<0x140>(v, v); return v; }
; __device__ __forceinline__ float silu_f(float x) { return x * __builtin_amdgcn_rcpf(1.f + __expf(-x)); }
; template <bool DRY> __device__ __forceinline__ void ssd_unit(const Args& A, char* lds, int b, int h) {
;     ...
;         for (int pi = 0; pi < 2; ++pi)
; #pragma unroll
;             for (int r = 0; r < 4; ++r) { const int l = lt * 16 + 4 * fq + r, p = (pt0 + pi) * 16 + fr;
;                 const float y = ya[pi][r] + Dh * bf2f(XS[l * 72 + p]);
;                 const float z = bf2f(zv[pi][r]); const float gt = y * silu_f(z);
;                 gts[pi][r] = (unsigned short)f2bf(gt); sqs[pi][r] = row_sum16(gt * gt); }
	v_lshlrev_b32_e32 v46, 16, v46
	v_fma_f32 v36, v54, v46, v36
	v_add_f32_e32 v44, 1.0, v44
	v_rcp_f32_e32 v46, v44
	v_lshlrev_b32_e32 v44, 16, v84
	v_mul_f32_e32 v49, 0xbfb8aa3b, v44
	v_exp_f32_e32 v49, v49
	v_mul_f32_e32 v45, v46, v45
	v_mul_f32_e32 v36, v45, v36
	v_and_b32_e32 v45, 0xffff0000, v84
	v_add_f32_e32 v46, 1.0, v49
	v_mul_f32_e32 v49, 0xbfb8aa3b, v45
	v_exp_f32_e32 v50, v49
	v_lshlrev_b32_e32 v49, 16, v48
	v_lshlrev_b32_e32 v48, 16, v47
	v_rcp_f32_e32 v46, v46
	v_add_f32_e32 v47, 1.0, v50
	v_rcp_f32_e32 v47, v47
	v_mov_b32_e32 v50, v37
	v_mov_b32_e32 v51, v38
	v_pk_fma_f32 v[48:49], v[54:55], v[48:49], v[50:51]
	v_pk_mul_f32 v[44:45], v[46:47], v[44:45]
	v_lshlrev_b32_e32 v91, 16, v90
	v_pk_mul_f32 v[44:45], v[44:45], v[48:49]
	v_lshlrev_b32_e32 v90, 16, v87
	v_pk_mov_b32 v[46:47], v[44:45], v[44:45] op_sel:[1,0]
	s_nop 0
	v_mov_b32_e32 v37, v47
	v_pk_mul_f32 v[48:49], v[36:37], v[36:37]
	v_lshlrev_b32_e32 v47, 16, v82
	v_fma_f32 v40, v54, v47, v40
	v_mov_b32_dpp v48, v48 quad_perm:[1,0,3,2] row_mask:0xf bank_mask:0xf
	v_mov_b32_dpp v49, v49 quad_perm:[1,0,3,2] row_mask:0xf bank_mask:0xf
	v_pk_fma_f32 v[48:49], v[36:37], v[36:37], v[48:49]
	v_lshlrev_b32_e32 v37, 16, v96
	v_mul_f32_e32 v38, 0xbfb8aa3b, v37
	v_exp_f32_e32 v38, v38
	v_mov_b32_e32 v50, v48
	v_mov_b32_e32 v51, v49
	v_add_f32_e32 v38, 1.0, v38
	v_rcp_f32_e32 v38, v38
	v_mov_b32_dpp v50, v50 quad_perm:[2,3,0,1] row_mask:0xf bank_mask:0xf
	v_mov_b32_dpp v51, v51 quad_perm:[2,3,0,1] row_mask:0xf bank_mask:0xf
	v_pk_add_f32 v[48:49], v[48:49], v[50:51]
	v_mul_f32_e32 v37, v38, v37
	v_mul_f32_e32 v47, v37, v40
	v_mul_f32_e32 v37, 0xbfb8aa3b, v88
	v_exp_f32_e32 v37, v37
	v_mul_f32_e32 v38, 0xbfb8aa3b, v89
	v_exp_f32_e32 v38, v38
	v_mov_b32_e32 v40, v41
	v_add_f32_e32 v37, 1.0, v37
	v_rcp_f32_e32 v86, v37
	v_add_f32_e32 v37, 1.0, v38
	v_rcp_f32_e32 v87, v37
	v_mov_b32_e32 v41, v42
	v_pk_fma_f32 v[40:41], v[54:55], v[90:91], v[40:41]
	v_mov_b32_e32 v42, v39
	v_pk_mul_f32 v[86:87], v[86:87], v[88:89]
	v_pk_mul_f32 v[82:83], v[46:47], v[46:47]
	v_pk_mul_f32 v[86:87], v[86:87], v[40:41]
	v_mov_b32_e32 v50, v48
	v_pk_mul_f32 v[40:41], v[86:87], v[86:87]
	v_mov_b32_dpp v82, v82 quad_perm:[1,0,3,2] row_mask:0xf bank_mask:0xf
	v_mov_b32_dpp v83, v83 quad_perm:[1,0,3,2] row_mask:0xf bank_mask:0xf
	v_mov_b32_dpp v40, v40 quad_perm:[1,0,3,2] row_mask:0xf bank_mask:0xf
	v_mov_b32_dpp v41, v41 quad_perm:[1,0,3,2] row_mask:0xf bank_mask:0xf
	v_pk_fma_f32 v[40:41], v[86:87], v[86:87], v[40:41]
	v_pk_fma_f32 v[82:83], v[46:47], v[46:47], v[82:83]
	v_mov_b32_e32 v88, v40
	v_mov_b32_e32 v89, v41
	v_mov_b32_e32 v84, v82
	v_mov_b32_dpp v88, v88 quad_perm:[2,3,0,1] row_mask:0xf bank_mask:0xf
	v_mov_b32_dpp v89, v89 quad_perm:[2,3,0,1] row_mask:0xf bank_mask:0xf
	v_pk_add_f32 v[40:41], v[40:41], v[88:89]
	v_mov_b32_e32 v85, v83
	v_mov_b32_e32 v88, v40
	v_mov_b32_e32 v89, v41
	v_mov_b32_dpp v84, v84 quad_perm:[2,3,0,1] row_mask:0xf bank_mask:0xf
	v_mov_b32_dpp v88, v88 row_half_mirror row_mask:0xf bank_mask:0xf
	v_mov_b32_dpp v89, v89 row_half_mirror row_mask:0xf bank_mask:0xf
	v_pk_add_f32 v[88:89], v[40:41], v[88:89]
	v_lshlrev_b32_e32 v40, 16, v94
	v_mul_f32_e32 v37, 0xbfb8aa3b, v40
	v_lshlrev_b32_e32 v41, 16, v95
	v_exp_f32_e32 v37, v37
	v_mul_f32_e32 v38, 0xbfb8aa3b, v41
	v_exp_f32_e32 v38, v38
	v_lshlrev_b32_e32 v95, 16, v93
	v_add_f32_e32 v37, 1.0, v37
	v_rcp_f32_e32 v92, v37
	v_add_f32_e32 v37, 1.0, v38
	v_rcp_f32_e32 v93, v37
	v_lshlrev_b32_e32 v94, 16, v97
	v_pk_fma_f32 v[38:39], v[54:55], v[94:95], v[42:43]
	v_mov_b32_dpp v85, v85 quad_perm:[2,3,0,1] row_mask:0xf bank_mask:0xf
	v_pk_mul_f32 v[40:41], v[92:93], v[40:41]
	v_pk_add_f32 v[82:83], v[82:83], v[84:85]
	v_pk_mul_f32 v[92:93], v[40:41], v[38:39]
	v_mov_b32_e32 v51, v49
	v_pk_mul_f32 v[38:39], v[92:93], v[92:93]
	v_mov_b32_e32 v84, v82
	v_mov_b32_e32 v85, v83
	v_mov_b32_dpp v38, v38 quad_perm:[1,0,3,2] row_mask:0xf bank_mask:0xf
	v_mov_b32_dpp v39, v39 quad_perm:[1,0,3,2] row_mask:0xf bank_mask:0xf
	v_pk_fma_f32 v[38:39], v[92:93], v[92:93], v[38:39]
	v_mov_b32_dpp v50, v50 row_half_mirror row_mask:0xf bank_mask:0xf
	v_mov_b32_e32 v40, v38
	v_mov_b32_e32 v41, v39
	v_mov_b32_dpp v51, v51 row_half_mirror row_mask:0xf bank_mask:0xf
	v_mov_b32_dpp v40, v40 quad_perm:[2,3,0,1] row_mask:0xf bank_mask:0xf
	v_mov_b32_dpp v41, v41 quad_perm:[2,3,0,1] row_mask:0xf bank_mask:0xf
	v_pk_add_f32 v[38:39], v[38:39], v[40:41]
	v_mov_b32_dpp v84, v84 row_half_mirror row_mask:0xf bank_mask:0xf
	v_mov_b32_e32 v40, v38
	v_mov_b32_e32 v41, v39
	v_mov_b32_dpp v85, v85 row_half_mirror row_mask:0xf bank_mask:0xf
	v_mov_b32_dpp v40, v40 row_half_mirror row_mask:0xf bank_mask:0xf
	v_mov_b32_dpp v41, v41 row_half_mirror row_mask:0xf bank_mask:0xf
	v_pk_add_f32 v[48:49], v[48:49], v[50:51]
	v_pk_add_f32 v[82:83], v[82:83], v[84:85]
	v_pk_add_f32 v[94:95], v[38:39], v[40:41]
	v_mov_b32_e32 v50, v48
	v_mov_b32_e32 v51, v49
	v_mov_b32_e32 v84, v82
	v_mov_b32_e32 v85, v83
	v_mov_b32_e32 v90, v88
	v_mov_b32_e32 v91, v89
	v_mov_b32_e32 v96, v94
	v_mov_b32_e32 v97, v95
	v_mov_b32_dpp v50, v50 row_mirror row_mask:0xf bank_mask:0xf
	v_mov_b32_dpp v51, v51 row_mirror row_mask:0xf bank_mask:0xf
	v_mov_b32_dpp v84, v84 row_mirror row_mask:0xf bank_mask:0xf
	v_mov_b32_dpp v85, v85 row_mirror row_mask:0xf bank_mask:0xf
	v_mov_b32_dpp v90, v90 row_mirror row_mask:0xf bank_mask:0xf
	v_mov_b32_dpp v91, v91 row_mirror row_mask:0xf bank_mask:0xf
	v_mov_b32_dpp v96, v96 row_mirror row_mask:0xf bank_mask:0xf
	v_mov_b32_dpp v97, v97 row_mirror row_mask:0xf bank_mask:0xf
